# v69 + all four GEMM tails: late fragment loads hoisted into dead VGPR tuples (40 loads), vmcnt waits recomputed from dataflow
# speedup vs baseline: 1.0003x; 1.0003x over previous
; template <class Epi, int K>
; __device__ __forceinline__ void gemm_tail(LAS unsigned char* lds, const bf16_t* A, const bf16_t* Bt, const int N, const Epi& E, const int bid, const int G, const int tid_in) {
;     ...
;         const bf16_t* ap = A + (size_t)(MMAIN + i16) * K + wid * kw + 8 * kq;
;         const bf16_t* bp = Bt + (size_t)(256 * pn + 32 * wc + 8 * (i16 >> 2) + (i16 & 3)) * K + wid * kw + 8 * kq;
;         f32x4 acc[2][4][2];
; #pragma unroll
;         for (int bj = 0; bj < 2; ++bj)
; #pragma unroll
;             for (int m = 0; m < 4; ++m)
; #pragma unroll
;                 for (int n = 0; n < 2; ++n) acc[bj][m][n] = (f32x4){0.f, 0.f, 0.f, 0.f};
; #pragma unroll
;         for (int sb = 0; sb < NS; sb += 4) {
;             bf16x8 af[4][4], bf[4][2][2];
; #pragma unroll
;             for (int s = 0; s < 4; ++s) if (sb + s < NS) {
; #pragma unroll
;                 for (int m = 0; m < 4; ++m) af[s][m] = *(const bf16x8*)(ap + (size_t)(16 * m) * K + 32 * (sb + s));
; #pragma unroll
;                 for (int bj = 0; bj < 2; ++bj)
; #pragma unroll
;                     for (int n = 0; n < 2; ++n) bf[s][bj][n] = *(const bf16x8*)(bp + (size_t)(128 * bj + 4 * n) * K + 32 * (sb + s));
;             }
; #pragma unroll
;             for (int s = 0; s < 4; ++s) if (sb + s < NS) {
; #pragma unroll
;                 for (int bj = 0; bj < 2; ++bj)
; #pragma unroll
;                     for (int m = 0; m < 4; ++m)
; #pragma unroll
;                         for (int n = 0; n < 2; ++n) acc[bj][m][n] = __builtin_amdgcn_mfma_f32_16x16x32_bf16(bf[s][bj][n], af[s][m], acc[bj][m][n], 0, 0, 0);
;             }
.LBB0_322:
	s_ashr_i32 s6, s3, 2
	s_and_b32 s27, s3, 3
	s_lshl_b32 s10, s6, 8
	v_lshl_or_b32 v0, s27, 5, v193
	v_or_b32_e32 v2, s10, v0
	v_ashrrev_i32_e32 v3, 31, v2
	v_lshlrev_b64 v[2:3], 11, v[2:3]
	v_lshl_add_u64 v[2:3], v[86:87], 0, v[2:3]
	v_add_co_u32_e32 v4, vcc, s76, v2
	global_load_dwordx4 v[6:9], v[2:3], off
	global_load_dwordx4 v[14:17], v[84:85], off
	global_load_dwordx4 v[18:21], v[152:153], off
	v_addc_co_u32_e32 v5, vcc, 0, v3, vcc
	v_add_co_u32_e32 v12, vcc, s78, v2
	global_load_dwordx4 v[42:45], v[4:5], off
	global_load_dwordx4 v[78:81], v[2:3], off offset:64
	v_addc_co_u32_e32 v13, vcc, 0, v3, vcc
	v_add_co_u32_e32 v10, vcc, s79, v2
	global_load_dwordx4 v[58:61], v[12:13], off
	s_nop 0
	v_addc_co_u32_e32 v11, vcc, 0, v3, vcc
	global_load_dwordx4 v[66:69], v[10:11], off
	global_load_dwordx4 v[26:29], v[154:155], off
	global_load_dwordx4 v[34:37], v[156:157], off
	global_load_dwordx4 v[202:205], v[160:161], off
	global_load_dwordx4 v[224:227], v[162:163], off
	global_load_dwordx4 v[198:201], v[158:159], off
	global_load_dwordx4 v[244:247], v[10:11], off offset:64
	global_load_dwordx4 v[248:251], v[172:173], off
	s_waitcnt vmcnt(12)
	v_mfma_f32_16x16x32_bf16 v[22:25], v[6:9], v[14:17], 0
	s_waitcnt vmcnt(11)
	v_mfma_f32_16x16x32_bf16 v[30:33], v[6:9], v[18:21], 0
	s_waitcnt vmcnt(6)
	v_mfma_f32_16x16x32_bf16 v[38:41], v[6:9], v[26:29], 0
	s_waitcnt vmcnt(5)
	v_mfma_f32_16x16x32_bf16 v[6:9], v[6:9], v[34:37], 0
	v_mfma_f32_16x16x32_bf16 v[46:49], v[42:45], v[14:17], 0
	v_mfma_f32_16x16x32_bf16 v[50:53], v[42:45], v[18:21], 0
	v_mfma_f32_16x16x32_bf16 v[54:57], v[42:45], v[26:29], 0
	v_mfma_f32_16x16x32_bf16 v[42:45], v[42:45], v[34:37], 0
	v_mfma_f32_16x16x32_bf16 v[62:65], v[58:61], v[14:17], 0
	v_mfma_f32_16x16x32_bf16 v[14:17], v[66:69], v[14:17], 0
	v_mfma_f32_16x16x32_bf16 v[70:73], v[58:61], v[18:21], 0
	v_mfma_f32_16x16x32_bf16 v[18:21], v[66:69], v[18:21], 0
	v_mfma_f32_16x16x32_bf16 v[74:77], v[58:61], v[26:29], 0
	v_mfma_f32_16x16x32_bf16 v[26:29], v[66:69], v[26:29], 0
	v_mfma_f32_16x16x32_bf16 v[58:61], v[58:61], v[34:37], 0
	v_mfma_f32_16x16x32_bf16 v[34:37], v[66:69], v[34:37], 0
	global_load_dwordx4 v[66:69], v[84:85], off offset:64
	s_waitcnt vmcnt(0)
	v_mfma_f32_16x16x32_bf16 v[22:25], v[78:81], v[66:69], v[22:25]
	v_mfma_f32_16x16x32_bf16 v[30:33], v[78:81], v[198:201], v[30:33]
	v_mfma_f32_16x16x32_bf16 v[38:41], v[78:81], v[202:205], v[38:41]
	v_mfma_f32_16x16x32_bf16 v[6:9], v[78:81], v[224:227], v[6:9]
	global_load_dwordx4 v[78:81], v[4:5], off offset:64
	s_waitcnt vmcnt(0)
	v_mfma_f32_16x16x32_bf16 v[46:49], v[78:81], v[66:69], v[46:49]
	v_mfma_f32_16x16x32_bf16 v[50:53], v[78:81], v[198:201], v[50:53]
	v_mfma_f32_16x16x32_bf16 v[54:57], v[78:81], v[202:205], v[54:57]
	v_mfma_f32_16x16x32_bf16 v[42:45], v[78:81], v[224:227], v[42:45]
	global_load_dwordx4 v[78:81], v[12:13], off offset:64
	s_waitcnt vmcnt(0)
	v_mfma_f32_16x16x32_bf16 v[62:65], v[78:81], v[66:69], v[62:65]
	v_mfma_f32_16x16x32_bf16 v[14:17], v[244:247], v[66:69], v[14:17]
	v_mfma_f32_16x16x32_bf16 v[66:69], v[78:81], v[198:201], v[70:73]
	v_mfma_f32_16x16x32_bf16 v[18:21], v[244:247], v[198:201], v[18:21]
	global_load_dwordx4 v[186:189], v[4:5], off offset:128
	v_mfma_f32_16x16x32_bf16 v[70:73], v[78:81], v[202:205], v[74:77]
	s_nop 2
	global_load_dwordx4 v[74:77], v[2:3], off offset:128
	v_mfma_f32_16x16x32_bf16 v[58:61], v[78:81], v[224:227], v[58:61]
	global_load_dwordx4 v[78:81], v[84:85], off offset:128
	v_mfma_f32_16x16x32_bf16 v[34:37], v[244:247], v[224:227], v[34:37]
	global_load_dwordx4 v[224:227], v[166:167], off
	v_mfma_f32_16x16x32_bf16 v[26:29], v[244:247], v[202:205], v[26:29]
	global_load_dwordx4 v[202:205], v[164:165], off
	s_waitcnt vmcnt(1)
	v_mfma_f32_16x16x32_bf16 v[228:231], v[186:189], v[224:227], v[54:57]
	s_nop 2
	global_load_dwordx4 v[54:57], v[168:169], off
	v_mfma_f32_16x16x32_bf16 v[22:25], v[74:77], v[78:81], v[22:25]
	v_mfma_f32_16x16x32_bf16 v[46:49], v[186:189], v[78:81], v[46:49]
	s_waitcnt vmcnt(1)
	v_mfma_f32_16x16x32_bf16 v[30:33], v[74:77], v[202:205], v[30:33]
	v_mfma_f32_16x16x32_bf16 v[50:53], v[186:189], v[202:205], v[50:53]
	v_mfma_f32_16x16x32_bf16 v[38:41], v[74:77], v[224:227], v[38:41]
	s_waitcnt vmcnt(0)
	v_mfma_f32_16x16x32_bf16 v[6:9], v[74:77], v[54:57], v[6:9]
	global_load_dwordx4 v[74:77], v[12:13], off offset:128
	v_mfma_f32_16x16x32_bf16 v[42:45], v[186:189], v[54:57], v[42:45]
	global_load_dwordx4 v[186:189], v[10:11], off offset:128
	s_waitcnt vmcnt(0)
	v_mfma_f32_16x16x32_bf16 v[14:17], v[186:189], v[78:81], v[14:17]
	v_mfma_f32_16x16x32_bf16 v[232:235], v[74:77], v[202:205], v[66:69]
	v_mfma_f32_16x16x32_bf16 v[202:205], v[186:189], v[202:205], v[18:21]
	v_mfma_f32_16x16x32_bf16 v[236:239], v[74:77], v[224:227], v[70:73]
	v_mfma_f32_16x16x32_bf16 v[26:29], v[186:189], v[224:227], v[26:29]
	v_mfma_f32_16x16x32_bf16 v[224:227], v[74:77], v[54:57], v[58:61]
	s_nop 2
	global_load_dwordx4 v[58:61], v[2:3], off offset:192
	v_mfma_f32_16x16x32_bf16 v[186:189], v[186:189], v[54:57], v[34:37]
	s_nop 2
	global_load_dwordx4 v[34:37], v[84:85], off offset:192
	s_waitcnt vmcnt(0)
	v_mfma_f32_16x16x32_bf16 v[70:73], v[58:61], v[34:37], v[22:25]
	global_load_dwordx4 v[2:5], v[4:5], off offset:192
	s_waitcnt vmcnt(0)
	v_mfma_f32_16x16x32_bf16 v[66:69], v[2:5], v[34:37], v[46:49]
	s_nop 2
	global_load_dwordx4 v[46:49], v[170:171], off
	v_mfma_f32_16x16x32_bf16 v[22:25], v[58:61], v[248:251], v[38:41]
	s_nop 2
	global_load_dwordx4 v[38:41], v[174:175], off
	s_waitcnt vmcnt(1)
	v_mfma_f32_16x16x32_bf16 v[50:53], v[2:5], v[46:49], v[50:53]
	v_mfma_f32_16x16x32_bf16 v[18:21], v[2:5], v[248:251], v[228:231]
	s_waitcnt vmcnt(0)
	v_mfma_f32_16x16x32_bf16 v[2:5], v[2:5], v[38:41], v[42:45]
	s_nop 2
	global_load_dwordx4 v[42:45], v[12:13], off offset:192
	v_mfma_f32_16x16x32_bf16 v[62:65], v[74:77], v[78:81], v[62:65]
	global_load_dwordx4 v[10:13], v[10:11], off offset:192
	s_waitcnt vmcnt(1)
	v_mfma_f32_16x16x32_bf16 v[74:77], v[42:45], v[34:37], v[62:65]
	s_waitcnt vmcnt(0)
	v_mfma_f32_16x16x32_bf16 v[78:81], v[10:13], v[34:37], v[14:17]
	global_load_dwordx4 v[34:37], v[176:177], off offset:16
	s_nop 1
	global_load_dwordx4 v[14:17], v[176:177], off
	v_mfma_f32_16x16x32_bf16 v[54:57], v[58:61], v[46:49], v[30:33]
	s_waitcnt vmcnt(0)
	v_pk_add_f32 v[36:37], v[16:17], v[36:37]
	v_pk_add_f32 v[34:35], v[14:15], v[34:35]
	v_mfma_f32_16x16x32_bf16 v[6:9], v[58:61], v[38:41], v[6:9]
	v_add_f32_e32 v0, v34, v35
	v_add_f32_e32 v34, v36, v37
	v_add_f32_e32 v0, v0, v34
	ds_bpermute_b32 v34, v208, v0
	v_mfma_f32_16x16x32_bf16 v[62:65], v[42:45], v[46:49], v[232:235]
	v_mfma_f32_16x16x32_bf16 v[58:61], v[10:13], v[46:49], v[202:205]
	v_mfma_f32_16x16x32_bf16 v[30:33], v[42:45], v[248:251], v[236:239]
	v_mfma_f32_16x16x32_bf16 v[26:29], v[10:13], v[248:251], v[26:29]
	v_mfma_f32_16x16x32_bf16 v[14:17], v[42:45], v[38:41], v[224:227]
	v_mfma_f32_16x16x32_bf16 v[10:13], v[10:13], v[38:41], v[186:189]
	s_and_saveexec_b64 s[14:15], s[36:37]
	s_cbranch_execz .LBB0_324
; #define LAS __attribute__((address_space(3)))
; __device__ __forceinline__ void rs_commit(LAS unsigned char* lds, const PrepRegs& r, int ui, int tid) {
;     const f32x4 s4 = r.a + r.b; float s = (s4[0] + s4[1]) + (s4[2] + s4[3]); s += __shfl_xor(s, 1);
;     if ((tid & 1) == 0) ((LAS float*)(lds + LDS_RSTAB))[(ui & 1) * 256 + (tid >> 1)] = rsqrtf(s * (1.0f / DM) + EPS);
; }
	s_waitcnt lgkmcnt(0)
	v_add_f32_e32 v0, v0, v34
	v_fmamk_f32 v0, v0, 0x3a800000, v214
	s_mov_b32 s11, 0x800000
	v_mul_f32_e32 v34, 0x4b800000, v0
	v_cmp_gt_f32_e32 vcc, s11, v0
	s_nop 1
	v_cndmask_b32_e32 v0, v0, v34, vcc
	v_rsq_f32_e32 v0, v0
	s_nop 0
	v_mul_f32_e32 v34, 0x45800000, v0
	v_cndmask_b32_e32 v0, v0, v34, vcc
	ds_write_b32 v209, v0

; template <class Epi, int K>
; __device__ __forceinline__ void gemm_tail(LAS unsigned char* lds, const bf16_t* A, const bf16_t* Bt, const int N, const Epi& E, const int bid, const int G, const int tid_in) {
;     ...
;         const bf16_t* ap = A + (size_t)(MMAIN + i16) * K + wid * kw + 8 * kq;
;         const bf16_t* bp = Bt + (size_t)(256 * pn + 32 * wc + 8 * (i16 >> 2) + (i16 & 3)) * K + wid * kw + 8 * kq;
;         f32x4 acc[2][4][2];
; #pragma unroll
;         for (int bj = 0; bj < 2; ++bj)
; #pragma unroll
;             for (int m = 0; m < 4; ++m)
; #pragma unroll
;                 for (int n = 0; n < 2; ++n) acc[bj][m][n] = (f32x4){0.f, 0.f, 0.f, 0.f};
; #pragma unroll
;         for (int sb = 0; sb < NS; sb += 4) {
;             bf16x8 af[4][4], bf[4][2][2];
; #pragma unroll
;             for (int s = 0; s < 4; ++s) if (sb + s < NS) {
; #pragma unroll
;                 for (int m = 0; m < 4; ++m) af[s][m] = *(const bf16x8*)(ap + (size_t)(16 * m) * K + 32 * (sb + s));
; #pragma unroll
;                 for (int bj = 0; bj < 2; ++bj)
; #pragma unroll
;                     for (int n = 0; n < 2; ++n) bf[s][bj][n] = *(const bf16x8*)(bp + (size_t)(128 * bj + 4 * n) * K + 32 * (sb + s));
;             }
; #pragma unroll
;             for (int s = 0; s < 4; ++s) if (sb + s < NS) {
; #pragma unroll
;                 for (int bj = 0; bj < 2; ++bj)
; #pragma unroll
;                     for (int m = 0; m < 4; ++m)
; #pragma unroll
;                         for (int n = 0; n < 2; ++n) acc[bj][m][n] = __builtin_amdgcn_mfma_f32_16x16x32_bf16(bf[s][bj][n], af[s][m], acc[bj][m][n], 0, 0, 0);
;             }
.LBB0_707:
	s_and_b32 s14, s3, 3
	s_lshl_b32 s6, s3, 6
	s_and_b32 s8, s6, 0xffffff00
	v_lshl_or_b32 v2, s14, 5, v143
	v_or_b32_e32 v2, s8, v2
	v_ashrrev_i32_e32 v3, 31, v2
	v_lshlrev_b64 v[2:3], 11, v[2:3]
	v_lshl_add_u64 v[2:3], v[92:93], 0, v[2:3]
	v_add_co_u32_e32 v4, vcc, s27, v2
	global_load_dwordx4 v[6:9], v[2:3], off
	global_load_dwordx4 v[14:17], v[90:91], off
	global_load_dwordx4 v[18:21], v[100:101], off
	v_addc_co_u32_e32 v5, vcc, 0, v3, vcc
	global_load_dwordx4 v[26:29], v[102:103], off
	global_load_dwordx4 v[78:81], v[90:91], off offset:64
	global_load_dwordx4 v[34:37], v[104:105], off
	global_load_dwordx4 v[82:85], v[106:107], off
	global_load_dwordx4 v[42:45], v[4:5], off
	global_load_dwordx4 v[70:73], v[2:3], off offset:64
	global_load_dwordx4 v[86:89], v[108:109], off
	global_load_dwordx4 v[146:149], v[110:111], off
	v_add_co_u32_e32 v10, vcc, s33, v2
	global_load_dwordx4 v[162:165], v[118:119], off
	global_load_dwordx4 v[166:169], v[4:5], off offset:64
	global_load_dwordx4 v[170:173], v[2:3], off offset:128
	global_load_dwordx4 v[174:177], v[114:115], off
	global_load_dwordx4 v[178:181], v[90:91], off offset:128
	global_load_dwordx4 v[182:185], v[4:5], off offset:128
	global_load_dwordx4 v[186:189], v[112:113], off
	global_load_dwordx4 v[198:201], v[116:117], off
	global_load_dwordx4 v[202:205], v[90:91], off offset:192
	global_load_dwordx4 v[206:209], v[2:3], off offset:192
	global_load_dwordx4 v[222:225], v[4:5], off offset:192
	global_load_dwordx4 v[226:229], v[120:121], off
	global_load_dwordx4 v[230:233], v[122:123], off
	s_waitcnt vmcnt(22)
	v_mfma_f32_16x16x32_bf16 v[22:25], v[6:9], v[14:17], 0
	v_addc_co_u32_e32 v11, vcc, 0, v3, vcc
	v_add_co_u32_e32 v12, vcc, s42, v2
	s_waitcnt vmcnt(21)
	v_mfma_f32_16x16x32_bf16 v[30:33], v[6:9], v[18:21], 0
	v_addc_co_u32_e32 v13, vcc, 0, v3, vcc
	global_load_dwordx4 v[58:61], v[10:11], off
	s_waitcnt vmcnt(21)
	v_mfma_f32_16x16x32_bf16 v[38:41], v[6:9], v[26:29], 0
	s_andn2_b64 vcc, exec, s[4:5]
	global_load_dwordx4 v[150:153], v[12:13], off offset:64
	s_waitcnt vmcnt(20)
	v_mfma_f32_16x16x32_bf16 v[6:9], v[6:9], v[34:37], 0
	s_waitcnt vmcnt(17)
	v_mfma_f32_16x16x32_bf16 v[22:25], v[70:73], v[78:81], v[22:25]
	v_mfma_f32_16x16x32_bf16 v[30:33], v[70:73], v[82:85], v[30:33]
	s_waitcnt vmcnt(16)
	v_mfma_f32_16x16x32_bf16 v[38:41], v[70:73], v[86:89], v[38:41]
	s_waitcnt vmcnt(15)
	v_mfma_f32_16x16x32_bf16 v[6:9], v[70:73], v[146:149], v[6:9]
	global_load_dwordx4 v[70:73], v[12:13], off
	v_mfma_f32_16x16x32_bf16 v[46:49], v[42:45], v[14:17], 0
	v_mfma_f32_16x16x32_bf16 v[50:53], v[42:45], v[18:21], 0
	v_mfma_f32_16x16x32_bf16 v[54:57], v[42:45], v[26:29], 0
	v_mfma_f32_16x16x32_bf16 v[42:45], v[42:45], v[34:37], 0
	s_waitcnt vmcnt(2)
	v_mfma_f32_16x16x32_bf16 v[62:65], v[58:61], v[14:17], 0
	v_mfma_f32_16x16x32_bf16 v[66:69], v[58:61], v[18:21], 0
	v_mfma_f32_16x16x32_bf16 v[74:77], v[58:61], v[26:29], 0
	v_mfma_f32_16x16x32_bf16 v[58:61], v[58:61], v[34:37], 0
	s_waitcnt vmcnt(0)
	v_mfma_f32_16x16x32_bf16 v[14:17], v[70:73], v[14:17], 0
	v_mfma_f32_16x16x32_bf16 v[18:21], v[70:73], v[18:21], 0
	v_mfma_f32_16x16x32_bf16 v[26:29], v[70:73], v[26:29], 0
	v_mfma_f32_16x16x32_bf16 v[34:37], v[70:73], v[34:37], 0
	v_mfma_f32_16x16x32_bf16 v[46:49], v[166:169], v[78:81], v[46:49]
	v_mfma_f32_16x16x32_bf16 v[50:53], v[166:169], v[82:85], v[50:53]
	v_mfma_f32_16x16x32_bf16 v[54:57], v[166:169], v[86:89], v[54:57]
	v_mfma_f32_16x16x32_bf16 v[42:45], v[166:169], v[146:149], v[42:45]
	global_load_dwordx4 v[70:73], v[10:11], off offset:64
	s_waitcnt vmcnt(0)
; #define LAS __attribute__((address_space(3)))
;     __device__ __forceinline__ void prep_commit(LAS unsigned char* lds, const PrepRegs& r, int ui, int tid) const { rs_commit(lds, r, ui, tid); }
;     __device__ __forceinline__ void prep_commit(LAS unsigned char* lds, const PrepRegs& r, int ui, int tid) const { rs_commit(lds, r, ui, tid); }
; template <class Epi, int K>
; __device__ __forceinline__ void gemm_tail(LAS unsigned char* lds, const bf16_t* A, const bf16_t* Bt, const int N, const Epi& E, const int bid, const int G, const int tid_in) {
;     ...
;             for (int s = 0; s < 4; ++s) if (sb + s < NS) {
; #pragma unroll
;                 for (int bj = 0; bj < 2; ++bj)
; #pragma unroll
;                     for (int m = 0; m < 4; ++m)
; #pragma unroll
;                         for (int n = 0; n < 2; ++n) acc[bj][m][n] = __builtin_amdgcn_mfma_f32_16x16x32_bf16(bf[s][bj][n], af[s][m], acc[bj][m][n], 0, 0, 0);
;             }
;         }
;         E.prep_commit(lds, prt, 0, tid);
;         LAS f32x4* P = (LAS f32x4*)lds;
; #pragma unroll
;         for (int bj = 0; bj < 2; ++bj)
; #pragma unroll
;             for (int m = 0; m < 4; ++m)
; #pragma unroll
;                 for (int n = 0; n < 2; ++n) P[(wid * 16 + bj * 8 + m * 2 + n) * 64 + lane] = acc[bj][m][n];
;         __syncthreads();
	v_mfma_f32_16x16x32_bf16 v[62:65], v[70:73], v[78:81], v[62:65]
	v_mfma_f32_16x16x32_bf16 v[66:69], v[70:73], v[82:85], v[66:69]
	v_mfma_f32_16x16x32_bf16 v[74:77], v[70:73], v[86:89], v[74:77]
	v_mfma_f32_16x16x32_bf16 v[58:61], v[70:73], v[146:149], v[58:61]
	v_mfma_f32_16x16x32_bf16 v[34:37], v[150:153], v[146:149], v[34:37]
	v_mfma_f32_16x16x32_bf16 v[14:17], v[150:153], v[78:81], v[14:17]
	v_mfma_f32_16x16x32_bf16 v[18:21], v[150:153], v[82:85], v[18:21]
	v_mfma_f32_16x16x32_bf16 v[26:29], v[150:153], v[86:89], v[26:29]
	v_mfma_f32_16x16x32_bf16 v[150:153], v[170:173], v[174:177], v[38:41]
	s_nop 2
	v_mfma_f32_16x16x32_bf16 v[22:25], v[170:173], v[178:181], v[22:25]
	v_mfma_f32_16x16x32_bf16 v[30:33], v[170:173], v[186:189], v[30:33]
	v_mfma_f32_16x16x32_bf16 v[6:9], v[170:173], v[198:201], v[6:9]
	global_load_dwordx4 v[70:73], v[10:11], off offset:128
	v_mfma_f32_16x16x32_bf16 v[46:49], v[182:185], v[178:181], v[46:49]
	v_mfma_f32_16x16x32_bf16 v[50:53], v[182:185], v[186:189], v[50:53]
	v_mfma_f32_16x16x32_bf16 v[54:57], v[182:185], v[174:177], v[54:57]
	v_mfma_f32_16x16x32_bf16 v[42:45], v[182:185], v[198:201], v[42:45]
	s_waitcnt vmcnt(0)
	v_mfma_f32_16x16x32_bf16 v[82:85], v[70:73], v[178:181], v[62:65]
	s_nop 2
	global_load_dwordx4 v[62:65], v[12:13], off offset:128
	s_waitcnt vmcnt(0)
	v_mfma_f32_16x16x32_bf16 v[14:17], v[62:65], v[178:181], v[14:17]
	v_mfma_f32_16x16x32_bf16 v[66:69], v[70:73], v[186:189], v[66:69]
	v_mfma_f32_16x16x32_bf16 v[74:77], v[70:73], v[174:177], v[74:77]
	v_mfma_f32_16x16x32_bf16 v[26:29], v[62:65], v[174:177], v[26:29]
	v_mfma_f32_16x16x32_bf16 v[146:149], v[70:73], v[198:201], v[58:61]
	s_nop 0
	v_mfma_f32_16x16x32_bf16 v[154:157], v[62:65], v[198:201], v[34:37]
	v_mfma_f32_16x16x32_bf16 v[34:37], v[222:225], v[162:165], v[50:53]
	s_nop 2
	v_mfma_f32_16x16x32_bf16 v[86:89], v[62:65], v[186:189], v[18:21]
	v_mfma_f32_16x16x32_bf16 v[58:61], v[206:209], v[202:205], v[22:25]
	v_mfma_f32_16x16x32_bf16 v[22:25], v[206:209], v[226:229], v[150:153]
	s_nop 2
	global_load_dwordx4 v[150:153], v[10:11], off offset:192
	s_nop 0
	global_load_dwordx4 v[10:13], v[12:13], off offset:192
	v_mfma_f32_16x16x32_bf16 v[18:21], v[222:225], v[226:229], v[54:57]
	s_nop 2
	v_mfma_f32_16x16x32_bf16 v[62:65], v[222:225], v[202:205], v[46:49]
	v_mfma_f32_16x16x32_bf16 v[38:41], v[206:209], v[162:165], v[30:33]
	v_mfma_f32_16x16x32_bf16 v[6:9], v[206:209], v[230:233], v[6:9]
	v_mfma_f32_16x16x32_bf16 v[2:5], v[222:225], v[230:233], v[42:45]
	s_waitcnt vmcnt(1)
	v_mfma_f32_16x16x32_bf16 v[70:73], v[150:153], v[202:205], v[82:85]
	s_waitcnt vmcnt(0)
	v_mfma_f32_16x16x32_bf16 v[78:81], v[10:13], v[202:205], v[14:17]
	s_nop 1
	v_add_u32_e32 v82, s2, v144
	ds_write_b128 v82, v[58:61]
	ds_write_b128 v82, v[62:65] offset:1024
	ds_write_b128 v82, v[38:41] offset:2048
	ds_write_b128 v82, v[34:37] offset:3072
	ds_write_b128 v82, v[22:25] offset:4096
	ds_write_b128 v82, v[18:21] offset:5120
	v_mfma_f32_16x16x32_bf16 v[46:49], v[150:153], v[162:165], v[66:69]
	ds_write_b128 v82, v[6:9] offset:6144
	ds_write_b128 v82, v[2:5] offset:7168
	ds_write_b128 v82, v[70:73] offset:8192
	v_mfma_f32_16x16x32_bf16 v[42:45], v[10:13], v[162:165], v[86:89]
	ds_write_b128 v82, v[78:81] offset:9216
	s_nop 2
	ds_write_b128 v82, v[46:49] offset:10240
	s_nop 2
	ds_write_b128 v82, v[42:45] offset:11264
	v_mfma_f32_16x16x32_bf16 v[30:33], v[150:153], v[226:229], v[74:77]
	v_mfma_f32_16x16x32_bf16 v[26:29], v[10:13], v[226:229], v[26:29]
	v_mfma_f32_16x16x32_bf16 v[14:17], v[150:153], v[230:233], v[146:149]
	s_nop 5
	ds_write_b128 v82, v[30:33] offset:12288
	ds_write_b128 v82, v[26:29] offset:13312
	ds_write_b128 v82, v[14:17] offset:14336
	v_mfma_f32_16x16x32_bf16 v[10:13], v[10:13], v[230:233], v[154:157]
	s_nop 7
	ds_write_b128 v82, v[10:13] offset:15360
	s_waitcnt lgkmcnt(0)
	s_barrier
	s_cbranch_vccnz .LBB0_706
	s_movk_i32 s8, 0x4000

; template <class Epi, int K>
; __device__ __forceinline__ void gemm_tail(LAS unsigned char* lds, const bf16_t* A, const bf16_t* Bt, const int N, const Epi& E, const int bid, const int G, const int tid_in) {
;     ...
;         const bf16_t* ap = A + (size_t)(MMAIN + i16) * K + wid * kw + 8 * kq;
;         const bf16_t* bp = Bt + (size_t)(256 * pn + 32 * wc + 8 * (i16 >> 2) + (i16 & 3)) * K + wid * kw + 8 * kq;
;         f32x4 acc[2][4][2];
; #pragma unroll
;         for (int bj = 0; bj < 2; ++bj)
; #pragma unroll
;             for (int m = 0; m < 4; ++m)
; #pragma unroll
;                 for (int n = 0; n < 2; ++n) acc[bj][m][n] = (f32x4){0.f, 0.f, 0.f, 0.f};
; #pragma unroll
;         for (int sb = 0; sb < NS; sb += 4) {
;             bf16x8 af[4][4], bf[4][2][2];
; #pragma unroll
;             for (int s = 0; s < 4; ++s) if (sb + s < NS) {
; #pragma unroll
;                 for (int m = 0; m < 4; ++m) af[s][m] = *(const bf16x8*)(ap + (size_t)(16 * m) * K + 32 * (sb + s));
; #pragma unroll
;                 for (int bj = 0; bj < 2; ++bj)
; #pragma unroll
;                     for (int n = 0; n < 2; ++n) bf[s][bj][n] = *(const bf16x8*)(bp + (size_t)(128 * bj + 4 * n) * K + 32 * (sb + s));
;             }
; #pragma unroll
;             for (int s = 0; s < 4; ++s) if (sb + s < NS) {
; #pragma unroll
;                 for (int bj = 0; bj < 2; ++bj)
; #pragma unroll
;                     for (int m = 0; m < 4; ++m)
; #pragma unroll
;                         for (int n = 0; n < 2; ++n) acc[bj][m][n] = __builtin_amdgcn_mfma_f32_16x16x32_bf16(bf[s][bj][n], af[s][m], acc[bj][m][n], 0, 0, 0);
;             }
.LBB0_1010:
	s_and_b32 s14, s3, 3
	s_lshl_b32 s6, s3, 6
	s_and_b32 s8, s6, 0xffffff00
	v_lshl_or_b32 v2, s14, 5, v221
	v_or_b32_e32 v2, s8, v2
	s_movk_i32 s8, 0x1600
	v_mad_i64_i32 v[72:73], s[8:9], v2, s8, v[100:101]
	v_add_co_u32_e32 v70, vcc, 0x5000, v72
	global_load_dwordx4 v[18:21], v[72:73], off
	global_load_dwordx4 v[2:5], v[98:99], off
	global_load_dwordx4 v[6:9], v[108:109], off
	v_addc_co_u32_e32 v71, vcc, 0, v73, vcc
	global_load_dwordx4 v[10:13], v[110:111], off
	global_load_dwordx4 v[74:77], v[98:99], off offset:64
	global_load_dwordx4 v[14:17], v[112:113], off
	global_load_dwordx4 v[78:81], v[114:115], off
	global_load_dwordx4 v[26:29], v[70:71], off offset:2048
	global_load_dwordx4 v[62:65], v[72:73], off offset:64
	global_load_dwordx4 v[82:85], v[116:117], off
	global_load_dwordx4 v[86:89], v[118:119], off
	v_add_co_u32_e32 v210, vcc, 0xb0000, v72
	global_load_dwordx4 v[236:239], v[98:99], off offset:576
	global_load_dwordx4 v[240:243], v[70:71], off offset:2112
	global_load_dwordx4 v[244:247], v[72:73], off offset:128
	global_load_dwordx4 v[248:251], v[98:99], off offset:128
	s_waitcnt vmcnt(13)
	v_mfma_f32_16x16x32_bf16 v[46:49], v[18:21], v[2:5], 0
	v_addc_co_u32_e32 v211, vcc, 0, v73, vcc
	v_add_co_u32_e32 v208, vcc, 0xb5000, v72
	s_waitcnt vmcnt(12)
	v_mfma_f32_16x16x32_bf16 v[50:53], v[18:21], v[6:9], 0
	s_nop 0
	v_addc_co_u32_e32 v209, vcc, 0, v73, vcc
	global_load_dwordx4 v[66:69], v[210:211], off
	s_waitcnt vmcnt(12)
	v_mfma_f32_16x16x32_bf16 v[54:57], v[18:21], v[10:13], 0
	global_load_dwordx4 v[90:93], v[208:209], off offset:2112
	s_andn2_b64 vcc, exec, s[4:5]
	s_waitcnt vmcnt(11)
	v_mfma_f32_16x16x32_bf16 v[58:61], v[18:21], v[14:17], 0
	global_load_dwordx4 v[232:235], v[208:209], off offset:2624
	s_waitcnt vmcnt(9)
	v_mfma_f32_16x16x32_bf16 v[46:49], v[62:65], v[74:77], v[46:49]
	v_mfma_f32_16x16x32_bf16 v[50:53], v[62:65], v[78:81], v[50:53]
	s_waitcnt vmcnt(8)
	v_mfma_f32_16x16x32_bf16 v[54:57], v[62:65], v[82:85], v[54:57]
	s_waitcnt vmcnt(7)
	v_mfma_f32_16x16x32_bf16 v[58:61], v[62:65], v[86:89], v[58:61]
	global_load_dwordx4 v[62:65], v[208:209], off offset:2048
	v_mfma_f32_16x16x32_bf16 v[18:21], v[26:29], v[2:5], 0
	v_mfma_f32_16x16x32_bf16 v[22:25], v[26:29], v[6:9], 0
	v_mfma_f32_16x16x32_bf16 v[34:37], v[26:29], v[10:13], 0
	v_mfma_f32_16x16x32_bf16 v[38:41], v[26:29], v[14:17], 0
	s_waitcnt vmcnt(3)
	v_mfma_f32_16x16x32_bf16 v[42:45], v[66:69], v[2:5], 0
	v_mfma_f32_16x16x32_bf16 v[26:29], v[66:69], v[6:9], 0
	v_mfma_f32_16x16x32_bf16 v[30:33], v[66:69], v[10:13], 0
	v_mfma_f32_16x16x32_bf16 v[66:69], v[66:69], v[14:17], 0
	s_waitcnt vmcnt(0)
	v_mfma_f32_16x16x32_bf16 v[2:5], v[62:65], v[2:5], 0
	v_mfma_f32_16x16x32_bf16 v[6:9], v[62:65], v[6:9], 0
	v_mfma_f32_16x16x32_bf16 v[10:13], v[62:65], v[10:13], 0
	v_mfma_f32_16x16x32_bf16 v[14:17], v[62:65], v[14:17], 0
	v_mfma_f32_16x16x32_bf16 v[18:21], v[240:243], v[74:77], v[18:21]
	v_mfma_f32_16x16x32_bf16 v[22:25], v[240:243], v[78:81], v[22:25]
	v_mfma_f32_16x16x32_bf16 v[34:37], v[240:243], v[82:85], v[34:37]
	v_mfma_f32_16x16x32_bf16 v[38:41], v[240:243], v[86:89], v[38:41]
	global_load_dwordx4 v[62:65], v[210:211], off offset:64
	s_waitcnt vmcnt(0)
	v_mfma_f32_16x16x32_bf16 v[42:45], v[62:65], v[74:77], v[42:45]
	v_mfma_f32_16x16x32_bf16 v[26:29], v[62:65], v[78:81], v[26:29]
	v_mfma_f32_16x16x32_bf16 v[30:33], v[62:65], v[82:85], v[30:33]
	v_mfma_f32_16x16x32_bf16 v[62:65], v[62:65], v[86:89], v[66:69]
	s_nop 2
	v_mfma_f32_16x16x32_bf16 v[2:5], v[90:93], v[74:77], v[2:5]
	v_mfma_f32_16x16x32_bf16 v[6:9], v[90:93], v[78:81], v[6:9]
	global_load_dwordx4 v[78:81], v[70:71], off offset:2176
	v_mfma_f32_16x16x32_bf16 v[10:13], v[90:93], v[82:85], v[10:13]
	global_load_dwordx4 v[82:85], v[120:121], off
	v_mfma_f32_16x16x32_bf16 v[14:17], v[90:93], v[86:89], v[14:17]
	global_load_dwordx4 v[86:89], v[122:123], off
	global_load_dwordx4 v[90:93], v[124:125], off
	v_mfma_f32_16x16x32_bf16 v[46:49], v[244:247], v[248:251], v[46:49]
	s_waitcnt vmcnt(2)
	v_mfma_f32_16x16x32_bf16 v[50:53], v[244:247], v[82:85], v[50:53]
	s_waitcnt vmcnt(1)
	v_mfma_f32_16x16x32_bf16 v[54:57], v[244:247], v[86:89], v[54:57]
	s_waitcnt vmcnt(0)
	v_mfma_f32_16x16x32_bf16 v[58:61], v[244:247], v[90:93], v[58:61]
	global_load_dwordx4 v[66:69], v[210:211], off offset:128
	v_mfma_f32_16x16x32_bf16 v[18:21], v[78:81], v[248:251], v[18:21]
	v_mfma_f32_16x16x32_bf16 v[22:25], v[78:81], v[82:85], v[22:25]
	v_mfma_f32_16x16x32_bf16 v[34:37], v[78:81], v[86:89], v[34:37]
	v_mfma_f32_16x16x32_bf16 v[38:41], v[78:81], v[90:93], v[38:41]
	global_load_dwordx4 v[78:81], v[208:209], off offset:2176
	s_waitcnt vmcnt(1)
	v_mfma_f32_16x16x32_bf16 v[42:45], v[66:69], v[248:251], v[42:45]
	v_mfma_f32_16x16x32_bf16 v[26:29], v[66:69], v[82:85], v[26:29]
	v_mfma_f32_16x16x32_bf16 v[30:33], v[66:69], v[86:89], v[30:33]
	v_mfma_f32_16x16x32_bf16 v[62:65], v[66:69], v[90:93], v[62:65]
	global_load_dwordx4 v[66:69], v[72:73], off offset:192
	s_waitcnt vmcnt(1)
	v_mfma_f32_16x16x32_bf16 v[2:5], v[78:81], v[248:251], v[2:5]
	global_load_dwordx4 v[74:77], v[98:99], off offset:192
	v_mfma_f32_16x16x32_bf16 v[6:9], v[78:81], v[82:85], v[6:9]
	global_load_dwordx4 v[82:85], v[126:127], off
	v_mfma_f32_16x16x32_bf16 v[10:13], v[78:81], v[86:89], v[10:13]
	global_load_dwordx4 v[86:89], v[128:129], off
	v_mfma_f32_16x16x32_bf16 v[14:17], v[78:81], v[90:93], v[14:17]
	global_load_dwordx4 v[78:81], v[70:71], off offset:2240
	global_load_dwordx4 v[90:93], v[130:131], off
	s_waitcnt vmcnt(4)
	v_mfma_f32_16x16x32_bf16 v[46:49], v[66:69], v[74:77], v[46:49]
	s_waitcnt vmcnt(3)
	v_mfma_f32_16x16x32_bf16 v[50:53], v[66:69], v[82:85], v[50:53]
	s_waitcnt vmcnt(2)
; template <class Epi, int K>
; __device__ __forceinline__ void gemm_tail(LAS unsigned char* lds, const bf16_t* A, const bf16_t* Bt, const int N, const Epi& E, const int bid, const int G, const int tid_in) {
;     ...
;         for (int sb = 0; sb < NS; sb += 4) {
;             bf16x8 af[4][4], bf[4][2][2];
; #pragma unroll
;             for (int s = 0; s < 4; ++s) if (sb + s < NS) {
; #pragma unroll
;                 for (int m = 0; m < 4; ++m) af[s][m] = *(const bf16x8*)(ap + (size_t)(16 * m) * K + 32 * (sb + s));
; #pragma unroll
;                 for (int bj = 0; bj < 2; ++bj)
; #pragma unroll
;                     for (int n = 0; n < 2; ++n) bf[s][bj][n] = *(const bf16x8*)(bp + (size_t)(128 * bj + 4 * n) * K + 32 * (sb + s));
;             }
; #pragma unroll
;             for (int s = 0; s < 4; ++s) if (sb + s < NS) {
; #pragma unroll
;                 for (int bj = 0; bj < 2; ++bj)
; #pragma unroll
;                     for (int m = 0; m < 4; ++m)
; #pragma unroll
;                         for (int n = 0; n < 2; ++n) acc[bj][m][n] = __builtin_amdgcn_mfma_f32_16x16x32_bf16(bf[s][bj][n], af[s][m], acc[bj][m][n], 0, 0, 0);
;             }
	v_mfma_f32_16x16x32_bf16 v[54:57], v[66:69], v[86:89], v[54:57]
	s_waitcnt vmcnt(0)
	v_mfma_f32_16x16x32_bf16 v[58:61], v[66:69], v[90:93], v[58:61]
	global_load_dwordx4 v[66:69], v[210:211], off offset:192
	v_mfma_f32_16x16x32_bf16 v[18:21], v[78:81], v[74:77], v[18:21]
	v_mfma_f32_16x16x32_bf16 v[22:25], v[78:81], v[82:85], v[22:25]
	v_mfma_f32_16x16x32_bf16 v[34:37], v[78:81], v[86:89], v[34:37]
	v_mfma_f32_16x16x32_bf16 v[38:41], v[78:81], v[90:93], v[38:41]
	global_load_dwordx4 v[78:81], v[208:209], off offset:2240
	s_waitcnt vmcnt(1)
	v_mfma_f32_16x16x32_bf16 v[42:45], v[66:69], v[74:77], v[42:45]
	v_mfma_f32_16x16x32_bf16 v[26:29], v[66:69], v[82:85], v[26:29]
	v_mfma_f32_16x16x32_bf16 v[30:33], v[66:69], v[86:89], v[30:33]
	v_mfma_f32_16x16x32_bf16 v[62:65], v[66:69], v[90:93], v[62:65]
	global_load_dwordx4 v[66:69], v[72:73], off offset:256
	s_waitcnt vmcnt(1)
	v_mfma_f32_16x16x32_bf16 v[2:5], v[78:81], v[74:77], v[2:5]
	global_load_dwordx4 v[74:77], v[98:99], off offset:256
	v_mfma_f32_16x16x32_bf16 v[6:9], v[78:81], v[82:85], v[6:9]
	global_load_dwordx4 v[82:85], v[132:133], off
	v_mfma_f32_16x16x32_bf16 v[10:13], v[78:81], v[86:89], v[10:13]
	global_load_dwordx4 v[86:89], v[134:135], off
	v_mfma_f32_16x16x32_bf16 v[14:17], v[78:81], v[90:93], v[14:17]
	global_load_dwordx4 v[78:81], v[70:71], off offset:2304
	global_load_dwordx4 v[90:93], v[136:137], off
	s_waitcnt vmcnt(4)
	v_mfma_f32_16x16x32_bf16 v[46:49], v[66:69], v[74:77], v[46:49]
	s_waitcnt vmcnt(3)
	v_mfma_f32_16x16x32_bf16 v[50:53], v[66:69], v[82:85], v[50:53]
	s_waitcnt vmcnt(2)
	v_mfma_f32_16x16x32_bf16 v[54:57], v[66:69], v[86:89], v[54:57]
	s_waitcnt vmcnt(0)
	v_mfma_f32_16x16x32_bf16 v[58:61], v[66:69], v[90:93], v[58:61]
	global_load_dwordx4 v[66:69], v[210:211], off offset:256
	v_mfma_f32_16x16x32_bf16 v[18:21], v[78:81], v[74:77], v[18:21]
	v_mfma_f32_16x16x32_bf16 v[22:25], v[78:81], v[82:85], v[22:25]
	v_mfma_f32_16x16x32_bf16 v[34:37], v[78:81], v[86:89], v[34:37]
	v_mfma_f32_16x16x32_bf16 v[38:41], v[78:81], v[90:93], v[38:41]
	global_load_dwordx4 v[78:81], v[208:209], off offset:2304
	s_waitcnt vmcnt(1)
	v_mfma_f32_16x16x32_bf16 v[42:45], v[66:69], v[74:77], v[42:45]
	v_mfma_f32_16x16x32_bf16 v[26:29], v[66:69], v[82:85], v[26:29]
	v_mfma_f32_16x16x32_bf16 v[30:33], v[66:69], v[86:89], v[30:33]
	v_mfma_f32_16x16x32_bf16 v[62:65], v[66:69], v[90:93], v[62:65]
	global_load_dwordx4 v[66:69], v[72:73], off offset:320
	s_waitcnt vmcnt(1)
	v_mfma_f32_16x16x32_bf16 v[2:5], v[78:81], v[74:77], v[2:5]
	global_load_dwordx4 v[74:77], v[98:99], off offset:320
	v_mfma_f32_16x16x32_bf16 v[6:9], v[78:81], v[82:85], v[6:9]
	global_load_dwordx4 v[82:85], v[138:139], off
	v_mfma_f32_16x16x32_bf16 v[10:13], v[78:81], v[86:89], v[10:13]
	global_load_dwordx4 v[86:89], v[140:141], off
	v_mfma_f32_16x16x32_bf16 v[14:17], v[78:81], v[90:93], v[14:17]
	global_load_dwordx4 v[78:81], v[70:71], off offset:2368
	global_load_dwordx4 v[90:93], v[142:143], off
	s_waitcnt vmcnt(4)
	v_mfma_f32_16x16x32_bf16 v[46:49], v[66:69], v[74:77], v[46:49]
	s_waitcnt vmcnt(3)
	v_mfma_f32_16x16x32_bf16 v[50:53], v[66:69], v[82:85], v[50:53]
	s_waitcnt vmcnt(2)
	v_mfma_f32_16x16x32_bf16 v[54:57], v[66:69], v[86:89], v[54:57]
	s_waitcnt vmcnt(0)
	v_mfma_f32_16x16x32_bf16 v[58:61], v[66:69], v[90:93], v[58:61]
	global_load_dwordx4 v[66:69], v[210:211], off offset:320
	v_mfma_f32_16x16x32_bf16 v[18:21], v[78:81], v[74:77], v[18:21]
	v_mfma_f32_16x16x32_bf16 v[22:25], v[78:81], v[82:85], v[22:25]
	v_mfma_f32_16x16x32_bf16 v[34:37], v[78:81], v[86:89], v[34:37]
	v_mfma_f32_16x16x32_bf16 v[38:41], v[78:81], v[90:93], v[38:41]
	global_load_dwordx4 v[78:81], v[208:209], off offset:2368
	s_waitcnt vmcnt(1)
	v_mfma_f32_16x16x32_bf16 v[42:45], v[66:69], v[74:77], v[42:45]
	v_mfma_f32_16x16x32_bf16 v[26:29], v[66:69], v[82:85], v[26:29]
	v_mfma_f32_16x16x32_bf16 v[30:33], v[66:69], v[86:89], v[30:33]
	v_mfma_f32_16x16x32_bf16 v[62:65], v[66:69], v[90:93], v[62:65]
	global_load_dwordx4 v[66:69], v[72:73], off offset:384
	s_waitcnt vmcnt(1)
	v_mfma_f32_16x16x32_bf16 v[2:5], v[78:81], v[74:77], v[2:5]
	global_load_dwordx4 v[74:77], v[98:99], off offset:384
	v_mfma_f32_16x16x32_bf16 v[6:9], v[78:81], v[82:85], v[6:9]
	global_load_dwordx4 v[82:85], v[144:145], off
	v_mfma_f32_16x16x32_bf16 v[10:13], v[78:81], v[86:89], v[10:13]
	global_load_dwordx4 v[86:89], v[146:147], off
	v_mfma_f32_16x16x32_bf16 v[14:17], v[78:81], v[90:93], v[14:17]
	global_load_dwordx4 v[78:81], v[70:71], off offset:2432
	global_load_dwordx4 v[90:93], v[148:149], off
	s_waitcnt vmcnt(4)
	v_mfma_f32_16x16x32_bf16 v[46:49], v[66:69], v[74:77], v[46:49]
	s_waitcnt vmcnt(3)
	v_mfma_f32_16x16x32_bf16 v[50:53], v[66:69], v[82:85], v[50:53]
	s_waitcnt vmcnt(2)
	v_mfma_f32_16x16x32_bf16 v[54:57], v[66:69], v[86:89], v[54:57]
	s_waitcnt vmcnt(0)
	v_mfma_f32_16x16x32_bf16 v[58:61], v[66:69], v[90:93], v[58:61]
	global_load_dwordx4 v[66:69], v[210:211], off offset:384
	v_mfma_f32_16x16x32_bf16 v[18:21], v[78:81], v[74:77], v[18:21]
	v_mfma_f32_16x16x32_bf16 v[22:25], v[78:81], v[82:85], v[22:25]
	v_mfma_f32_16x16x32_bf16 v[34:37], v[78:81], v[86:89], v[34:37]
	v_mfma_f32_16x16x32_bf16 v[38:41], v[78:81], v[90:93], v[38:41]
	global_load_dwordx4 v[78:81], v[208:209], off offset:2432
	s_waitcnt vmcnt(1)
	v_mfma_f32_16x16x32_bf16 v[42:45], v[66:69], v[74:77], v[42:45]
	v_mfma_f32_16x16x32_bf16 v[26:29], v[66:69], v[82:85], v[26:29]
	v_mfma_f32_16x16x32_bf16 v[30:33], v[66:69], v[86:89], v[30:33]
	v_mfma_f32_16x16x32_bf16 v[62:65], v[66:69], v[90:93], v[62:65]
	global_load_dwordx4 v[66:69], v[72:73], off offset:448
	s_waitcnt vmcnt(1)
; template <class Epi, int K>
; __device__ __forceinline__ void gemm_tail(LAS unsigned char* lds, const bf16_t* A, const bf16_t* Bt, const int N, const Epi& E, const int bid, const int G, const int tid_in) {
;     ...
;         for (int sb = 0; sb < NS; sb += 4) {
;             bf16x8 af[4][4], bf[4][2][2];
; #pragma unroll
;             for (int s = 0; s < 4; ++s) if (sb + s < NS) {
; #pragma unroll
;                 for (int m = 0; m < 4; ++m) af[s][m] = *(const bf16x8*)(ap + (size_t)(16 * m) * K + 32 * (sb + s));
; #pragma unroll
;                 for (int bj = 0; bj < 2; ++bj)
; #pragma unroll
;                     for (int n = 0; n < 2; ++n) bf[s][bj][n] = *(const bf16x8*)(bp + (size_t)(128 * bj + 4 * n) * K + 32 * (sb + s));
;             }
; #pragma unroll
;             for (int s = 0; s < 4; ++s) if (sb + s < NS) {
; #pragma unroll
;                 for (int bj = 0; bj < 2; ++bj)
; #pragma unroll
;                     for (int m = 0; m < 4; ++m)
; #pragma unroll
;                         for (int n = 0; n < 2; ++n) acc[bj][m][n] = __builtin_amdgcn_mfma_f32_16x16x32_bf16(bf[s][bj][n], af[s][m], acc[bj][m][n], 0, 0, 0);
;             }
	v_mfma_f32_16x16x32_bf16 v[2:5], v[78:81], v[74:77], v[2:5]
	global_load_dwordx4 v[74:77], v[98:99], off offset:448
	v_mfma_f32_16x16x32_bf16 v[6:9], v[78:81], v[82:85], v[6:9]
	global_load_dwordx4 v[82:85], v[150:151], off
	v_mfma_f32_16x16x32_bf16 v[10:13], v[78:81], v[86:89], v[10:13]
	global_load_dwordx4 v[86:89], v[152:153], off
	v_mfma_f32_16x16x32_bf16 v[14:17], v[78:81], v[90:93], v[14:17]
	global_load_dwordx4 v[78:81], v[70:71], off offset:2496
	global_load_dwordx4 v[90:93], v[154:155], off
	s_waitcnt vmcnt(4)
	v_mfma_f32_16x16x32_bf16 v[46:49], v[66:69], v[74:77], v[46:49]
	s_waitcnt vmcnt(3)
	v_mfma_f32_16x16x32_bf16 v[50:53], v[66:69], v[82:85], v[50:53]
	s_waitcnt vmcnt(2)
	v_mfma_f32_16x16x32_bf16 v[54:57], v[66:69], v[86:89], v[54:57]
	s_waitcnt vmcnt(0)
	v_mfma_f32_16x16x32_bf16 v[58:61], v[66:69], v[90:93], v[58:61]
	global_load_dwordx4 v[66:69], v[210:211], off offset:448
	v_mfma_f32_16x16x32_bf16 v[18:21], v[78:81], v[74:77], v[18:21]
	v_mfma_f32_16x16x32_bf16 v[22:25], v[78:81], v[82:85], v[22:25]
	v_mfma_f32_16x16x32_bf16 v[34:37], v[78:81], v[86:89], v[34:37]
	v_mfma_f32_16x16x32_bf16 v[38:41], v[78:81], v[90:93], v[38:41]
	global_load_dwordx4 v[78:81], v[208:209], off offset:2496
	s_waitcnt vmcnt(1)
	v_mfma_f32_16x16x32_bf16 v[42:45], v[66:69], v[74:77], v[42:45]
	v_mfma_f32_16x16x32_bf16 v[26:29], v[66:69], v[82:85], v[26:29]
	v_mfma_f32_16x16x32_bf16 v[30:33], v[66:69], v[86:89], v[30:33]
	v_mfma_f32_16x16x32_bf16 v[62:65], v[66:69], v[90:93], v[62:65]
	global_load_dwordx4 v[66:69], v[72:73], off offset:512
	s_waitcnt vmcnt(1)
	v_mfma_f32_16x16x32_bf16 v[2:5], v[78:81], v[74:77], v[2:5]
	global_load_dwordx4 v[74:77], v[98:99], off offset:512
	v_mfma_f32_16x16x32_bf16 v[6:9], v[78:81], v[82:85], v[6:9]
	global_load_dwordx4 v[82:85], v[156:157], off
	v_mfma_f32_16x16x32_bf16 v[10:13], v[78:81], v[86:89], v[10:13]
	global_load_dwordx4 v[86:89], v[158:159], off
	v_mfma_f32_16x16x32_bf16 v[14:17], v[78:81], v[90:93], v[14:17]
	global_load_dwordx4 v[90:93], v[160:161], off
	global_load_dwordx4 v[78:81], v[70:71], off offset:2560
	s_waitcnt vmcnt(4)
	v_mfma_f32_16x16x32_bf16 v[46:49], v[66:69], v[74:77], v[46:49]
	s_waitcnt vmcnt(3)
	v_mfma_f32_16x16x32_bf16 v[50:53], v[66:69], v[82:85], v[50:53]
	s_waitcnt vmcnt(2)
	v_mfma_f32_16x16x32_bf16 v[54:57], v[66:69], v[86:89], v[54:57]
	s_waitcnt vmcnt(1)
	v_mfma_f32_16x16x32_bf16 v[58:61], v[66:69], v[90:93], v[58:61]
	global_load_dwordx4 v[66:69], v[210:211], off offset:512
	s_waitcnt vmcnt(1)
	v_mfma_f32_16x16x32_bf16 v[18:21], v[78:81], v[74:77], v[18:21]
	v_mfma_f32_16x16x32_bf16 v[22:25], v[78:81], v[82:85], v[22:25]
	v_mfma_f32_16x16x32_bf16 v[34:37], v[78:81], v[86:89], v[34:37]
	v_mfma_f32_16x16x32_bf16 v[38:41], v[78:81], v[90:93], v[38:41]
	global_load_dwordx4 v[78:81], v[208:209], off offset:2560
	s_waitcnt vmcnt(1)
	v_mfma_f32_16x16x32_bf16 v[224:227], v[66:69], v[90:93], v[62:65]
	s_nop 2
	global_load_dwordx4 v[62:65], v[72:73], off offset:576
	v_mfma_f32_16x16x32_bf16 v[42:45], v[66:69], v[74:77], v[42:45]
	s_waitcnt vmcnt(1)
	v_mfma_f32_16x16x32_bf16 v[74:77], v[78:81], v[74:77], v[2:5]
	s_waitcnt vmcnt(0)
	v_mfma_f32_16x16x32_bf16 v[2:5], v[62:65], v[236:239], v[46:49]
	s_nop 2
	global_load_dwordx4 v[46:49], v[70:71], off offset:2624
	v_mfma_f32_16x16x32_bf16 v[94:97], v[78:81], v[82:85], v[6:9]
	s_waitcnt vmcnt(0)
	v_mfma_f32_16x16x32_bf16 v[6:9], v[46:49], v[236:239], v[18:21]
	s_nop 2
	global_load_dwordx4 v[18:21], v[162:163], off
	v_mfma_f32_16x16x32_bf16 v[198:201], v[78:81], v[86:89], v[10:13]
	v_mfma_f32_16x16x32_bf16 v[78:81], v[78:81], v[90:93], v[14:17]
	s_waitcnt vmcnt(0)
; #define LAS __attribute__((address_space(3)))
;     __device__ __forceinline__ void prep_commit(LAS unsigned char* lds, const PrepRegs& r, int ui, int tid) const { rs_commit(lds, r, ui, tid); }
;     __device__ __forceinline__ void prep_commit(LAS unsigned char* lds, const PrepRegs& r, int ui, int tid) const { rs_commit(lds, r, ui, tid); }
; template <class Epi, int K>
; __device__ __forceinline__ void gemm_tail(LAS unsigned char* lds, const bf16_t* A, const bf16_t* Bt, const int N, const Epi& E, const int bid, const int G, const int tid_in) {
;     ...
;             for (int s = 0; s < 4; ++s) if (sb + s < NS) {
; #pragma unroll
;                 for (int bj = 0; bj < 2; ++bj)
; #pragma unroll
;                     for (int m = 0; m < 4; ++m)
; #pragma unroll
;                         for (int n = 0; n < 2; ++n) acc[bj][m][n] = __builtin_amdgcn_mfma_f32_16x16x32_bf16(bf[s][bj][n], af[s][m], acc[bj][m][n], 0, 0, 0);
;             }
;         }
;         E.prep_commit(lds, prt, 0, tid);
;         LAS f32x4* P = (LAS f32x4*)lds;
; #pragma unroll
;         for (int bj = 0; bj < 2; ++bj)
; #pragma unroll
;             for (int m = 0; m < 4; ++m)
; #pragma unroll
;                 for (int n = 0; n < 2; ++n) P[(wid * 16 + bj * 8 + m * 2 + n) * 64 + lane] = acc[bj][m][n];
;         __syncthreads();
	v_mfma_f32_16x16x32_bf16 v[10:13], v[62:65], v[18:21], v[50:53]
	s_nop 2
	global_load_dwordx4 v[50:53], v[166:167], off
	v_mfma_f32_16x16x32_bf16 v[14:17], v[46:49], v[18:21], v[22:25]
	s_nop 2
	global_load_dwordx4 v[22:25], v[164:165], off
	v_mfma_f32_16x16x32_bf16 v[26:29], v[66:69], v[82:85], v[26:29]
	s_waitcnt vmcnt(0)
	v_mfma_f32_16x16x32_bf16 v[82:85], v[46:49], v[22:25], v[34:37]
	v_mfma_f32_16x16x32_bf16 v[90:93], v[46:49], v[50:53], v[38:41]
	global_load_dwordx4 v[46:49], v[210:211], off offset:576
	v_mfma_f32_16x16x32_bf16 v[30:33], v[66:69], v[86:89], v[30:33]
	v_mfma_f32_16x16x32_bf16 v[66:69], v[62:65], v[22:25], v[54:57]
	v_mfma_f32_16x16x32_bf16 v[54:57], v[232:235], v[18:21], v[94:97]
	s_nop 2
	global_load_dwordx4 v[94:97], v[72:73], off offset:640
	v_mfma_f32_16x16x32_bf16 v[86:89], v[62:65], v[50:53], v[58:61]
	s_waitcnt vmcnt(1)
	v_mfma_f32_16x16x32_bf16 v[58:61], v[46:49], v[18:21], v[26:29]
	v_mfma_f32_16x16x32_bf16 v[26:29], v[232:235], v[50:53], v[78:81]
	s_nop 2
	global_load_dwordx4 v[78:81], v[98:99], off offset:640
	v_mfma_f32_16x16x32_bf16 v[38:41], v[46:49], v[236:239], v[42:45]
	v_mfma_f32_16x16x32_bf16 v[42:45], v[46:49], v[22:25], v[30:33]
	v_mfma_f32_16x16x32_bf16 v[30:33], v[46:49], v[50:53], v[224:227]
	s_waitcnt vmcnt(0)
	v_mfma_f32_16x16x32_bf16 v[50:53], v[94:97], v[78:81], v[2:5]
	s_nop 2
	global_load_dwordx4 v[2:5], v[70:71], off offset:2688
	v_mfma_f32_16x16x32_bf16 v[62:65], v[232:235], v[236:239], v[74:77]
	s_nop 2
	global_load_dwordx4 v[74:77], v[168:169], off
	global_load_dwordx4 v[70:73], v[170:171], off
	s_waitcnt vmcnt(1)
	v_mfma_f32_16x16x32_bf16 v[18:21], v[2:5], v[74:77], v[14:17]
	s_waitcnt vmcnt(0)
	v_mfma_f32_16x16x32_bf16 v[14:17], v[94:97], v[70:73], v[66:69]
	s_nop 2
	global_load_dwordx4 v[66:69], v[172:173], off
	v_mfma_f32_16x16x32_bf16 v[34:37], v[232:235], v[22:25], v[198:201]
	v_mfma_f32_16x16x32_bf16 v[46:49], v[2:5], v[78:81], v[6:9]
	v_mfma_f32_16x16x32_bf16 v[22:25], v[94:97], v[74:77], v[10:13]
	v_mfma_f32_16x16x32_bf16 v[10:13], v[2:5], v[70:73], v[82:85]
	s_nop 2
	global_load_dwordx4 v[82:85], v[210:211], off offset:640
	s_waitcnt vmcnt(1)
	v_mfma_f32_16x16x32_bf16 v[6:9], v[94:97], v[66:69], v[86:89]
	s_nop 2
	global_load_dwordx4 v[86:89], v[208:209], off offset:2688
	v_mfma_f32_16x16x32_bf16 v[2:5], v[2:5], v[66:69], v[90:93]
	s_waitcnt vmcnt(1)
	v_mfma_f32_16x16x32_bf16 v[38:41], v[82:85], v[78:81], v[38:41]
	s_waitcnt vmcnt(0)
	v_mfma_f32_16x16x32_bf16 v[62:65], v[86:89], v[78:81], v[62:65]
	v_add_u32_e32 v78, s2, v222
	ds_write_b128 v78, v[50:53]
	ds_write_b128 v78, v[46:49] offset:1024
	ds_write_b128 v78, v[22:25] offset:2048
	ds_write_b128 v78, v[18:21] offset:3072
	ds_write_b128 v78, v[14:17] offset:4096
	ds_write_b128 v78, v[10:13] offset:5120
	v_mfma_f32_16x16x32_bf16 v[58:61], v[82:85], v[74:77], v[58:61]
	ds_write_b128 v78, v[6:9] offset:6144
	ds_write_b128 v78, v[2:5] offset:7168
	ds_write_b128 v78, v[38:41] offset:8192
	v_mfma_f32_16x16x32_bf16 v[54:57], v[86:89], v[74:77], v[54:57]
	ds_write_b128 v78, v[62:65] offset:9216
	s_nop 2
	ds_write_b128 v78, v[58:61] offset:10240
	s_nop 2
	ds_write_b128 v78, v[54:57] offset:11264
	v_mfma_f32_16x16x32_bf16 v[42:45], v[82:85], v[70:73], v[42:45]
	v_mfma_f32_16x16x32_bf16 v[34:37], v[86:89], v[70:73], v[34:37]
	v_mfma_f32_16x16x32_bf16 v[30:33], v[82:85], v[66:69], v[30:33]
	s_nop 5
	ds_write_b128 v78, v[42:45] offset:12288
	ds_write_b128 v78, v[34:37] offset:13312
	ds_write_b128 v78, v[30:33] offset:14336
	v_mfma_f32_16x16x32_bf16 v[26:29], v[86:89], v[66:69], v[26:29]
	s_nop 7
	ds_write_b128 v78, v[26:29] offset:15360
	s_waitcnt lgkmcnt(0)
	s_barrier
	s_cbranch_vccnz .LBB0_1009
	s_movk_i32 s8, 0x4000
